# diff-attn: lazy softmax rescale (reference max refreshed only when the tile max exceeds it by > 8 in log2 units; exact shift-invariance), on top of scale/max folded into MFMA (v_m16)
# speedup vs baseline: 1.0380x; 1.0317x over previous
.LBB0_50:
	v_max3_f32 v194, v166, v167, v168
	v_max3_f32 v195, v169, v162, v163
	v_max3_f32 v196, v164, v165, v158
	v_max3_f32 v194, v194, v159, v160
	v_max3_f32 v195, v195, v161, v154
	v_max3_f32 v196, v196, v155, v156
	v_max3_f32 v194, v194, v195, v157
	v_max_f32_e32 v194, v194, v196
	v_max3_f32 v195, v150, v151, v152
	v_max3_f32 v196, v153, v146, v147
	v_max3_f32 v199, v148, v149, v142
	v_max3_f32 v195, v195, v143, v144
	v_max3_f32 v196, v196, v145, v138
	v_max3_f32 v199, v199, v139, v140
	v_max3_f32 v195, v195, v196, v141
	v_max_f32_e32 v195, v195, v199
	v_mov_b32_e32 v196, v194
	v_mov_b32_e32 v199, v195
	s_nop 1
	v_permlane16_swap_b32_e32 v194, v196
	v_permlane16_swap_b32_e32 v195, v199
	v_max_f32_e32 v194, v194, v196
	v_max_f32_e32 v195, v195, v199
	v_mov_b32_e32 v196, v194
	v_mov_b32_e32 v199, v195
	s_nop 1
	v_permlane32_swap_b32_e32 v194, v196
	v_permlane32_swap_b32_e32 v195, v199
	v_max_f32_e32 v195, v195, v199
	v_max_f32_e32 v194, v194, v196
	s_cmpk_eq_i32 s54, 0xff80
	s_cbranch_scc1 .Lmy_first
	v_max_f32_e32 v196, v194, v195
	v_cmp_lt_f32_e32 vcc, 0x41000000, v196
	s_and_b64 vcc, exec, vcc
	s_cbranch_vccz .LBB0_52
	v_max_f32_e32 v199, 0, v194
	v_max_f32_e32 v201, 0, v195
	v_sub_f32_e32 v194, 0, v199
	v_exp_f32_e32 v194, v194
	s_nop 0
	v_pk_mul_f32 v[92:93], v[92:93], v[194:195] op_sel_hi:[1,0]
	v_pk_mul_f32 v[90:91], v[90:91], v[194:195] op_sel_hi:[1,0]
	v_pk_mul_f32 v[104:105], v[104:105], v[194:195] op_sel_hi:[1,0]
	v_pk_mul_f32 v[102:103], v[102:103], v[194:195] op_sel_hi:[1,0]
	v_pk_mul_f32 v[100:101], v[100:101], v[194:195] op_sel_hi:[1,0]
	v_pk_mul_f32 v[98:99], v[98:99], v[194:195] op_sel_hi:[1,0]
	v_pk_mul_f32 v[96:97], v[96:97], v[194:195] op_sel_hi:[1,0]
	v_pk_mul_f32 v[94:95], v[94:95], v[194:195] op_sel_hi:[1,0]
	v_pk_mul_f32 v[88:89], v[88:89], v[194:195] op_sel_hi:[1,0]
	v_pk_mul_f32 v[86:87], v[86:87], v[194:195] op_sel_hi:[1,0]
	v_pk_mul_f32 v[84:85], v[84:85], v[194:195] op_sel_hi:[1,0]
	v_pk_mul_f32 v[82:83], v[82:83], v[194:195] op_sel_hi:[1,0]
	v_pk_mul_f32 v[80:81], v[80:81], v[194:195] op_sel_hi:[1,0]
	v_pk_mul_f32 v[78:79], v[78:79], v[194:195] op_sel_hi:[1,0]
	v_pk_mul_f32 v[76:77], v[76:77], v[194:195] op_sel_hi:[1,0]
	v_pk_mul_f32 v[74:75], v[74:75], v[194:195] op_sel_hi:[1,0]
	v_sub_f32_e32 v195, 0, v201
	v_exp_f32_e32 v195, v195
	s_nop 0
	v_pk_mul_f32 v[178:179], v[178:179], v[194:195]
	v_mov_b32_e32 v194, v195
	v_pk_mul_f32 v[72:73], v[72:73], v[194:195] op_sel_hi:[1,0]
	v_pk_mul_f32 v[70:71], v[70:71], v[194:195] op_sel_hi:[1,0]
	v_pk_mul_f32 v[68:69], v[68:69], v[194:195] op_sel_hi:[1,0]
	v_pk_mul_f32 v[66:67], v[66:67], v[194:195] op_sel_hi:[1,0]
	v_pk_mul_f32 v[60:61], v[60:61], v[194:195] op_sel_hi:[1,0]
	v_pk_mul_f32 v[58:59], v[58:59], v[194:195] op_sel_hi:[1,0]
	v_pk_mul_f32 v[56:57], v[56:57], v[194:195] op_sel_hi:[1,0]
	v_pk_mul_f32 v[54:55], v[54:55], v[194:195] op_sel_hi:[1,0]
	v_pk_mul_f32 v[48:49], v[48:49], v[194:195] op_sel_hi:[1,0]
	v_pk_mul_f32 v[46:47], v[46:47], v[194:195] op_sel_hi:[1,0]
	v_pk_mul_f32 v[40:41], v[40:41], v[194:195] op_sel_hi:[1,0]
	v_pk_mul_f32 v[38:39], v[38:39], v[194:195] op_sel_hi:[1,0]
	v_pk_mul_f32 v[36:37], v[36:37], v[194:195] op_sel_hi:[1,0]
	v_pk_mul_f32 v[34:35], v[34:35], v[194:195] op_sel_hi:[1,0]
	v_pk_mul_f32 v[28:29], v[28:29], v[194:195] op_sel_hi:[1,0]
	v_pk_mul_f32 v[26:27], v[26:27], v[194:195] op_sel_hi:[1,0]
